# previous + P0 rmsnorm: norm gains preloaded once per wave instead of 7 serialized reloads per row
# speedup vs baseline: 1.0232x; 1.0196x over previous
; #define LAS __attribute__((address_space(3)))
; __device__ __forceinline__ unsigned cvt_pk_bf16(float lo, float hi) { unsigned r; asm volatile("v_cvt_pk_bf16_f32 %0, %1, %2" : "=v"(r) : "v"(lo), "v"(hi)); return r; }
; __device__ __forceinline__ void p0_prologue(const Params& p, LAS unsigned char* lds, int G) {
;     int tid_ = threadIdx.x; asm volatile("" : "+v"(tid_)); const int tid = tid_, lane = tid & 63, wave = tid >> 6;
;     LAS float* scr = (LAS float*)(lds + wave * 16384);
;     const int gw = blockIdx.x * 8 + wave, NGW = G * 8;
;     bf16_t* W1T = (bf16_t*)(p.ws + WS_W1T); bf16_t* W2T = (bf16_t*)(p.ws + WS_W2T); bf16_t* W3T = (bf16_t*)(p.ws + WS_W3T); bf16_t* W4T = (bf16_t*)(p.ws + WS_W4T);
;     constexpr int I1 = (DM / 64) * (N1 / 32), I2 = (GW / 64) * (DM / 32), I3 = (DM / 64) * (N3 / 32), I4 = (DM / 64) * (DM / 32);
;     bf16_t* h0 = (bf16_t*)(p.ws + WS_RA);
;     for (int m = gw; m < MT; m += NGW) {
;         const float* xrow = (m < MP) ? p.xp + (size_t)m * DM : p.xs + (size_t)(m - MP) * DM;
;         f32x4 v[8]; float s = 0.f;
; #pragma unroll
;         for (int j = 0; j < 8; ++j) { v[j] = __builtin_nontemporal_load((const f32x4*)(xrow + 4 * lane + 256 * j)); s += (v[j][0] * v[j][0] + v[j][1] * v[j][1]) + (v[j][2] * v[j][2] + v[j][3] * v[j][3]); }
;         const float rinv = __builtin_amdgcn_rsqf(wave_sum(s) * (1.0f / DM) + 1e-6f);
; #pragma unroll
;         for (int j = 0; j < 8; ++j) { const f32x4 gg = *(const f32x4*)(p.norm_g + 4 * lane + 256 * j);
;             u32x2 w; w.x = cvt_pk_bf16(v[j][0] * rinv * gg[0], v[j][1] * rinv * gg[1]); w.y = cvt_pk_bf16(v[j][2] * rinv * gg[2], v[j][3] * rinv * gg[3]);
;             *(u32x2*)(h0 + (size_t)m * DM + 4 * lane + 256 * j) = w; }
.LBB0_5:
	s_or_b64 exec, exec, s[0:1]
	s_add_u32 s20, s86, 0x6c00000
	s_addc_u32 s21, s87, 0
	v_mov_b32_e32 v37, v194
	s_lshl_b32 s0, s94, 3
	v_writelane_b32 v234, s0, 24
	v_ashrrev_i32_e32 v1, 6, v37
	v_add_u32_e32 v10, s0, v1
	v_readlane_b32 s0, v234, 1
	v_and_b32_e32 v36, 63, v37
	s_lshl_b32 s96, s0, 3
	s_movk_i32 s0, 0x2100
	v_readlane_b32 s1, v234, 2
	v_cmp_gt_i32_e32 vcc, s0, v10
	v_mbcnt_lo_u32_b32 v158, -1, 0
	v_lshlrev_b32_e32 v12, 3, v36
	s_and_saveexec_b64 s[0:1], vcc
	s_cbranch_execz .LBB0_10
	v_mbcnt_hi_u32_b32 v3, -1, v158
	v_and_b32_e32 v4, 64, v3
	v_add_u32_e32 v4, 64, v4
	v_xor_b32_e32 v5, 1, v3
	v_cmp_lt_i32_e32 vcc, v5, v4
	v_readlane_b32 s36, v234, 3
	v_mov_b32_e32 v15, 0
	v_cndmask_b32_e32 v5, v3, v5, vcc
	v_lshlrev_b32_e32 v38, 2, v5
	v_xor_b32_e32 v5, 2, v3
	v_cmp_lt_i32_e32 vcc, v5, v4
	v_lshlrev_b32_e32 v14, 4, v36
	v_readlane_b32 s44, v234, 11
	v_cndmask_b32_e32 v5, v3, v5, vcc
	v_lshlrev_b32_e32 v39, 2, v5
	v_xor_b32_e32 v5, 4, v3
	v_cmp_lt_i32_e32 vcc, v5, v4
	v_readlane_b32 s45, v234, 12
	s_mov_b64 s[4:5], 0x1000
	v_cndmask_b32_e32 v5, v3, v5, vcc
	v_lshlrev_b32_e32 v40, 2, v5
	v_xor_b32_e32 v5, 8, v3
	v_cmp_lt_i32_e32 vcc, v5, v4
	v_lshl_add_u64 v[18:19], s[44:45], 0, v[14:15]
	v_lshl_add_u64 v[20:21], v[18:19], 0, s[4:5]
	v_cndmask_b32_e32 v5, v3, v5, vcc
	v_lshlrev_b32_e32 v41, 2, v5
	v_xor_b32_e32 v5, 16, v3
	v_cmp_lt_i32_e32 vcc, v5, v4
	s_mov_b64 s[4:5], 0x1400
	v_lshl_add_u64 v[22:23], v[18:19], 0, s[4:5]
	v_cndmask_b32_e32 v5, v3, v5, vcc
	v_lshlrev_b32_e32 v42, 2, v5
	v_xor_b32_e32 v5, 32, v3
	v_cmp_lt_i32_e32 vcc, v5, v4
	s_mov_b64 s[4:5], 0x1800
	v_ashrrev_i32_e32 v11, 31, v10
	v_lshlrev_b32_e32 v2, 2, v36
	v_cndmask_b32_e32 v3, v3, v5, vcc
	v_mov_b32_e32 v13, v15
	v_readlane_b32 s37, v234, 4
	v_lshl_add_u64 v[24:25], v[18:19], 0, s[4:5]
	s_mov_b64 s[4:5], 0x1c00
	s_ashr_i32 s97, s96, 31
	v_lshlrev_b64 v[4:5], 13, v[10:11]
	v_lshlrev_b32_e32 v43, 2, v3
	v_lshl_add_u64 v[16:17], s[20:21], 0, v[12:13]
	v_lshl_add_u64 v[26:27], v[18:19], 0, s[4:5]
	v_lshl_add_u64 v[28:29], s[36:37], 0, v[4:5]
	s_lshl_b64 s[4:5], s[96:97], 13
	s_mov_b64 s[6:7], 0
	s_movk_i32 s10, 0x1fff
	v_lshlrev_b32_e32 v30, 2, v2
	v_mov_b32_e32 v31, v15
	s_movk_i32 s11, 0x1000
	v_mov_b32_e32 v13, 0x358637bd
	s_movk_i32 s12, 0x20ff
	v_mov_b64_e32 v[32:33], v[10:11]
	v_readlane_b32 s38, v234, 5
	v_readlane_b32 s39, v234, 6
	v_readlane_b32 s40, v234, 7
	v_readlane_b32 s41, v234, 8
	v_readlane_b32 s42, v234, 9
	v_readlane_b32 s43, v234, 10
	v_readlane_b32 s46, v234, 13
	v_readlane_b32 s47, v234, 14
	v_readlane_b32 s48, v234, 15
	v_readlane_b32 s49, v234, 16
	v_readlane_b32 s50, v234, 17
	v_readlane_b32 s51, v234, 18
	global_load_dwordx4 v[120:123], v[18:19], off
	global_load_dwordx4 v[124:127], v[18:19], off offset:1024
	global_load_dwordx4 v[128:131], v[18:19], off offset:2048
	global_load_dwordx4 v[132:135], v[18:19], off offset:3072
	global_load_dwordx4 v[136:139], v[20:21], off
	global_load_dwordx4 v[140:143], v[22:23], off
	global_load_dwordx4 v[144:147], v[24:25], off
	global_load_dwordx4 v[148:151], v[26:27], off
	s_branch .LBB0_8
; __device__ __forceinline__ unsigned cvt_pk_bf16(float lo, float hi) { unsigned r; asm volatile("v_cvt_pk_bf16_f32 %0, %1, %2" : "=v"(r) : "v"(lo), "v"(hi)); return r; }
; __device__ __forceinline__ float wave_sum(float v) {
; #pragma unroll
;     for (int o = 1; o < 64; o <<= 1) v += __shfl_xor(v, o);
;     return v;
; __device__ __forceinline__ void p0_prologue(const Params& p, LAS unsigned char* lds, int G) {
;     ...
;     for (int m = gw; m < MT; m += NGW) {
;         const float* xrow = (m < MP) ? p.xp + (size_t)m * DM : p.xs + (size_t)(m - MP) * DM;
;         f32x4 v[8]; float s = 0.f;
; #pragma unroll
;         for (int j = 0; j < 8; ++j) { v[j] = __builtin_nontemporal_load((const f32x4*)(xrow + 4 * lane + 256 * j)); s += (v[j][0] * v[j][0] + v[j][1] * v[j][1]) + (v[j][2] * v[j][2] + v[j][3] * v[j][3]); }
;         const float rinv = __builtin_amdgcn_rsqf(wave_sum(s) * (1.0f / DM) + 1e-6f);
; #pragma unroll
;         for (int j = 0; j < 8; ++j) { const f32x4 gg = *(const f32x4*)(p.norm_g + 4 * lane + 256 * j);
;             u32x2 w; w.x = cvt_pk_bf16(v[j][0] * rinv * gg[0], v[j][1] * rinv * gg[1]); w.y = cvt_pk_bf16(v[j][2] * rinv * gg[2], v[j][3] * rinv * gg[3]);
;             *(u32x2*)(h0 + (size_t)m * DM + 4 * lane + 256 * j) = w; }
;     }
.LBB0_7:
	s_or_b64 exec, exec, s[8:9]
	v_lshl_add_u64 v[2:3], v[2:3], 0, v[30:31]
	global_load_dwordx4 v[44:47], v[2:3], off nt
	global_load_dwordx4 v[48:51], v[2:3], off offset:1024 nt
	global_load_dwordx4 v[52:55], v[2:3], off offset:2048 nt
	global_load_dwordx4 v[56:59], v[2:3], off offset:3072 nt
	v_add_co_u32_e32 v2, vcc, s11, v2
	v_lshlrev_b64 v[34:35], 12, v[34:35]
	s_nop 0
	v_addc_co_u32_e32 v3, vcc, 0, v3, vcc
	global_load_dwordx4 v[60:63], v[2:3], off nt
	global_load_dwordx4 v[6:9], v[2:3], off offset:1024 nt
	global_load_dwordx4 v[64:67], v[2:3], off offset:2048 nt
	s_nop 0
	global_load_dwordx4 v[2:5], v[2:3], off offset:3072 nt
	s_nop 0
	v_lshl_add_u64 v[34:35], v[16:17], 0, v[34:35]
	v_lshl_add_u64 v[32:33], v[32:33], 0, s[96:97]
	v_cmp_lt_i32_e32 vcc, s12, v32
	s_or_b64 s[6:7], vcc, s[6:7]
	v_lshl_add_u64 v[28:29], v[28:29], 0, s[4:5]
	s_waitcnt vmcnt(7)
	v_mul_f32_e32 v11, v45, v45
	v_mul_f32_e32 v14, v47, v47
	s_waitcnt vmcnt(6)
	v_mul_f32_e32 v72, v49, v49
	v_mul_f32_e32 v73, v51, v51
	s_waitcnt vmcnt(5)
	v_mul_f32_e32 v74, v53, v53
	v_mul_f32_e32 v75, v55, v55
	v_fmac_f32_e32 v11, v44, v44
	v_fmac_f32_e32 v14, v46, v46
	v_fmac_f32_e32 v72, v48, v48
	v_fmac_f32_e32 v73, v50, v50
	s_waitcnt vmcnt(4)
	v_mul_f32_e32 v76, v57, v57
	v_mul_f32_e32 v77, v59, v59
	v_fmac_f32_e32 v74, v52, v52
	v_fmac_f32_e32 v75, v54, v54
	v_add_f32_e32 v11, v11, v14
	v_add_f32_e32 v14, v72, v73
	v_fmac_f32_e32 v76, v56, v56
	v_fmac_f32_e32 v77, v58, v58
	s_waitcnt vmcnt(3)
	v_mul_f32_e32 v78, v61, v61
	v_mul_f32_e32 v79, v63, v63
	v_add_f32_e32 v72, v74, v75
	v_add_f32_e32 v11, v11, v14
	s_waitcnt vmcnt(2)
	v_mul_f32_e32 v80, v7, v7
	v_mul_f32_e32 v81, v9, v9
	v_add_f32_e32 v73, v76, v77
	v_fmac_f32_e32 v78, v60, v60
	v_fmac_f32_e32 v79, v62, v62
	v_add_f32_e32 v11, v11, v72
	s_waitcnt vmcnt(1)
	v_mul_f32_e32 v82, v65, v65
	v_mul_f32_e32 v83, v67, v67
	v_fmac_f32_e32 v80, v6, v6
	v_fmac_f32_e32 v81, v8, v8
	v_add_f32_e32 v14, v78, v79
	v_add_f32_e32 v11, v11, v73
	s_waitcnt vmcnt(0)
	v_mul_f32_e32 v84, v3, v3
	v_mul_f32_e32 v85, v5, v5
	v_fmac_f32_e32 v82, v64, v64
	v_fmac_f32_e32 v83, v66, v66
	v_add_f32_e32 v74, v80, v81
	v_add_f32_e32 v11, v11, v14
	v_fmac_f32_e32 v84, v2, v2
	v_fmac_f32_e32 v85, v4, v4
	v_add_f32_e32 v75, v82, v83
	v_add_f32_e32 v11, v11, v74
	v_add_f32_e32 v76, v84, v85
	v_add_f32_e32 v11, v11, v75
	v_add_f32_e32 v11, v11, v76
	ds_bpermute_b32 v14, v38, v11
	s_waitcnt lgkmcnt(0)
	v_add_f32_e32 v11, v11, v14
	ds_bpermute_b32 v14, v39, v11
	s_waitcnt lgkmcnt(0)
	v_add_f32_e32 v11, v11, v14
	ds_bpermute_b32 v14, v40, v11
	s_waitcnt lgkmcnt(0)
	v_add_f32_e32 v11, v11, v14
	ds_bpermute_b32 v14, v41, v11
	s_waitcnt lgkmcnt(0)
	v_add_f32_e32 v11, v11, v14
	ds_bpermute_b32 v14, v42, v11
	s_waitcnt lgkmcnt(0)
	v_add_f32_e32 v11, v11, v14
	ds_bpermute_b32 v14, v43, v11
	s_waitcnt lgkmcnt(0)
	v_add_f32_e32 v11, v11, v14
	v_fmamk_f32 v11, v11, 0x3a000000, v13
	v_rsq_f32_e32 v11, v11
	s_nop 0
	v_mul_f32_e32 v14, v44, v11
	v_mul_f32_e32 v44, v45, v11
	v_mul_f32_e32 v45, v46, v11
	v_mul_f32_e32 v46, v47, v11
	v_mov_b32_e32 v68, v120
	v_mov_b32_e32 v69, v121
	v_mov_b32_e32 v70, v122
	v_mov_b32_e32 v71, v123
	v_mul_f32_e32 v44, v69, v44
	v_mul_f32_e32 v45, v70, v45
	v_mul_f32_e32 v14, v68, v14
	v_mul_f32_e32 v46, v71, v46
	v_cvt_pk_bf16_f32 v44, v14, v44
	v_cvt_pk_bf16_f32 v45, v45, v46
	global_store_dwordx2 v[34:35], v[44:45], off
	v_mov_b32_e32 v44, v124
	v_mov_b32_e32 v45, v125
	v_mov_b32_e32 v46, v126
	v_mov_b32_e32 v47, v127
	v_mul_f32_e32 v14, v48, v11
	v_mul_f32_e32 v48, v49, v11
	v_mul_f32_e32 v49, v50, v11
	v_mul_f32_e32 v50, v51, v11
	v_mul_f32_e32 v6, v6, v11
	v_mul_f32_e32 v7, v7, v11
	v_mul_f32_e32 v8, v8, v11
	v_mul_f32_e32 v9, v9, v11
	v_mul_f32_e32 v2, v2, v11
	v_mul_f32_e32 v3, v3, v11
	v_mul_f32_e32 v4, v4, v11
	v_mul_f32_e32 v5, v5, v11
	v_mul_f32_e32 v14, v44, v14
	v_mul_f32_e32 v44, v45, v48
	v_mul_f32_e32 v45, v46, v49
	v_mul_f32_e32 v46, v47, v50
	v_cvt_pk_bf16_f32 v44, v14, v44
	v_cvt_pk_bf16_f32 v45, v45, v46
	global_store_dwordx2 v[34:35], v[44:45], off offset:512
	v_mov_b32_e32 v44, v128
	v_mov_b32_e32 v45, v129
	v_mov_b32_e32 v46, v130
	v_mov_b32_e32 v47, v131
	v_mul_f32_e32 v14, v52, v11
	v_mul_f32_e32 v48, v53, v11
	v_mul_f32_e32 v49, v54, v11
	v_mul_f32_e32 v50, v55, v11
	v_mul_f32_e32 v14, v14, v44
	v_mul_f32_e32 v44, v48, v45
	v_mul_f32_e32 v45, v49, v46
	v_mul_f32_e32 v46, v50, v47
	v_cvt_pk_bf16_f32 v44, v14, v44
	v_cvt_pk_bf16_f32 v45, v45, v46
	global_store_dwordx2 v[34:35], v[44:45], off offset:1024
	v_mov_b32_e32 v44, v132
	v_mov_b32_e32 v45, v133
	v_mov_b32_e32 v46, v134
	v_mov_b32_e32 v47, v135
	v_mul_f32_e32 v14, v56, v11
	v_mul_f32_e32 v48, v57, v11
	v_mul_f32_e32 v49, v58, v11
	v_mul_f32_e32 v50, v59, v11
	v_mul_f32_e32 v14, v14, v44
	v_mul_f32_e32 v44, v48, v45
	v_mul_f32_e32 v45, v49, v46
	v_mul_f32_e32 v46, v50, v47
	v_cvt_pk_bf16_f32 v44, v14, v44
	v_cvt_pk_bf16_f32 v45, v45, v46
	global_store_dwordx2 v[34:35], v[44:45], off offset:1536
	v_mov_b32_e32 v44, v136
	v_mov_b32_e32 v45, v137
	v_mov_b32_e32 v46, v138
	v_mov_b32_e32 v47, v139
	v_mul_f32_e32 v14, v60, v11
	v_mul_f32_e32 v48, v61, v11
	v_mul_f32_e32 v49, v62, v11
	v_mul_f32_e32 v50, v63, v11
	v_mul_f32_e32 v14, v14, v44
	v_mul_f32_e32 v44, v48, v45
	v_mul_f32_e32 v45, v49, v46
	v_mul_f32_e32 v46, v50, v47
	v_cvt_pk_bf16_f32 v44, v14, v44
	v_cvt_pk_bf16_f32 v45, v45, v46
	global_store_dwordx2 v[34:35], v[44:45], off offset:2048
	v_mov_b32_e32 v44, v140
	v_mov_b32_e32 v45, v141
	v_mov_b32_e32 v46, v142
	v_mov_b32_e32 v47, v143
	v_mul_f32_e32 v14, v64, v11
	v_mul_f32_e32 v6, v6, v44
	v_mul_f32_e32 v7, v7, v45
	v_mul_f32_e32 v8, v8, v46
	v_mul_f32_e32 v9, v9, v47
	v_cvt_pk_bf16_f32 v6, v6, v7
	v_cvt_pk_bf16_f32 v7, v8, v9
	global_store_dwordx2 v[34:35], v[6:7], off offset:2560
	v_mov_b32_e32 v6, v144
	v_mov_b32_e32 v7, v145
	v_mov_b32_e32 v8, v146
	v_mov_b32_e32 v9, v147
	v_mul_f32_e32 v44, v65, v11
	v_mul_f32_e32 v45, v66, v11
	v_mul_f32_e32 v46, v67, v11
	v_mul_f32_e32 v6, v14, v6
	v_mul_f32_e32 v7, v44, v7
	v_mul_f32_e32 v8, v45, v8
	v_mul_f32_e32 v9, v46, v9
	v_cvt_pk_bf16_f32 v6, v6, v7
	v_cvt_pk_bf16_f32 v7, v8, v9
	global_store_dwordx2 v[34:35], v[6:7], off offset:3072
	v_mov_b32_e32 v6, v148
	v_mov_b32_e32 v7, v149
	v_mov_b32_e32 v8, v150
	v_mov_b32_e32 v9, v151
	v_mul_f32_e32 v2, v2, v6
	v_mul_f32_e32 v3, v3, v7
	v_mul_f32_e32 v4, v4, v8
	v_mul_f32_e32 v5, v5, v9
	v_cvt_pk_bf16_f32 v2, v2, v3
	v_cvt_pk_bf16_f32 v3, v4, v5
	global_store_dwordx2 v[34:35], v[2:3], off offset:3584
	s_andn2_b64 exec, exec, s[6:7]
	s_cbranch_execz .LBB0_10
